# in-proj tile order: rounds 1..5 (fp8) and 1..3 (bf16) run in reverse, so the mixer-input tiles are written last, closest to the mixer phase that reads them
# baseline (speedup 1.0000x reference)
.LBB0_208:
	s_add_i32 s87, s87, 1
	s_cmp_ge_i32 s87, s76
	s_mov_b64 s[66:67], 0
	s_cbranch_scc1 .LBB0_211
	s_sub_i32 s14, 6, s87
	s_cmp_lt_u32 s87, 6
	s_cselect_b32 s14, s14, s87
	s_mul_i32 s8, s14, s95
	s_mul_hi_u32 s9, s14, s26
	s_add_i32 s9, s9, s8
	s_mul_i32 s8, s14, s26
	s_add_u32 s14, s8, s64
	s_addc_u32 s15, s9, s7
	v_mov_b64_e32 v[0:1], 0x67f
	v_cmp_gt_i64_e32 vcc, s[14:15], v[0:1]
	s_cbranch_vccnz .LBB0_211
	s_ashr_i32 s8, s14, 31
	s_lshr_b32 s8, s8, 29
	s_add_i32 s8, s14, s8
	s_ashr_i32 s9, s8, 3
	s_and_b32 s8, s8, -8
	s_sub_i32 s8, s14, s8
	s_cmp_lt_i32 s8, 0
	s_movk_i32 s14, 0xd1
	s_cselect_b32 s14, s14, 0xd0
	s_mul_i32 s8, s8, s14
	s_add_i32 s8, s8, s9
	s_mul_hi_i32 s9, s8, 0x4ec4ec4f
	s_lshr_b32 s14, s9, 31
	s_ashr_i32 s9, s9, 6
	s_add_i32 s9, s9, s14
	s_lshl_b32 s14, s9, 3
	s_sub_i32 s15, 64, s14
	s_min_i32 s15, s15, 8
	s_abs_i32 s30, s15
	v_cvt_f32_u32_e32 v0, s30
	s_sub_i32 s34, 0, s30
	s_mulk_i32 s9, 0xd0
	s_sub_i32 s8, s8, s9
	v_rcp_iflag_f32_e32 v0, v0
	s_abs_i32 s9, s8
	s_xor_b32 s31, s8, s15
	s_ashr_i32 s31, s31, 31
	v_mul_f32_e32 v0, 0x4f7ffffe, v0
	v_cvt_u32_f32_e32 v0, v0
	s_mov_b64 s[66:67], -1
	v_readfirstlane_b32 s35, v0
	s_mul_i32 s34, s34, s35
	s_mul_hi_u32 s34, s35, s34
	s_add_i32 s35, s35, s34
	s_mul_hi_u32 s34, s9, s35
	s_mul_i32 s35, s34, s30
	s_sub_i32 s9, s9, s35
	s_add_i32 s44, s34, 1
	s_sub_i32 s35, s9, s30
	s_cmp_ge_u32 s9, s30
	s_cselect_b32 s34, s44, s34
	s_cselect_b32 s9, s35, s9
	s_add_i32 s35, s34, 1
	s_cmp_ge_u32 s9, s30
	s_cselect_b32 s9, s35, s34
	s_xor_b32 s9, s9, s31
	s_sub_i32 s9, s9, s31
	s_mul_i32 s15, s9, s15
	s_sub_i32 s8, s8, s15
	s_add_i32 s30, s14, s8
	s_cmp_lt_u32 s9, 18
	s_cselect_b32 s8, 12, 16
	s_cmp_gt_i32 s9, 7
	s_cselect_b32 s8, s8, 10
	s_add_i32 s34, s8, s9

.LBB0_644:
	s_mov_b32 s8, s86
	s_add_i32 s86, s86, 1
	s_cmp_gt_u32 s8, 0xffffe
	s_mov_b64 s[30:31], 0
	s_cbranch_scc1 .LBB0_651
	s_sub_i32 s18, 4, s86
	s_cmp_lt_u32 s86, 4
	s_cselect_b32 s18, s18, s86
	s_mul_i32 s8, s18, s95
	s_mul_hi_u32 s9, s18, s26
	s_add_i32 s9, s9, s8
	s_mul_i32 s8, s18, s26
	s_add_u32 s34, s8, s64
	s_addc_u32 s35, s9, s7
	s_cmp_eq_u32 s18, 2
	s_cselect_b32 s8, 0x80, 0
	s_xor_b32 s34, s34, s8
	v_mov_b64_e32 v[0:1], 0x3ff
	v_cmp_gt_i64_e32 vcc, s[34:35], v[0:1]
	s_cbranch_vccnz .LBB0_651
	s_ashr_i32 s8, s34, 31
	s_lshr_b32 s8, s8, 29
	s_add_i32 s8, s34, s8
	s_and_b32 s9, s8, -8
	s_sub_i32 s9, s34, s9
	s_cmp_gt_i32 s9, -1
	s_mov_b64 s[18:19], -1
	s_cbranch_scc0 .LBB0_648
	s_lshl_b32 s20, s9, 7
	s_mov_b64 s[18:19], 0
